# GEMM prologues: K-tile 1 stages requested before the first wait (vmcnt(2)->vmcnt(8)), on top of lean barrier stack
# baseline (speedup 1.0000x reference)
; #define PG8_STAGE(bufoff, gbase, voff) do { _Pragma("unroll") for (int _i = 0; _i < 2; ++_i) \
;         __builtin_amdgcn_global_load_lds((const unsigned*)((const char*)(gbase) + (voff)[_i]), (PG8_LAS unsigned*)(lds + (bufoff) + ldsw + _i * 8192), 16, 0, 0); } while (0)
; #define PG8_WAIT_V(n) asm volatile("s_waitcnt vmcnt(" #n ")" ::: "memory")
; #define PG8_BAR __builtin_amdgcn_s_barrier()
; template <class Epi, class Sched, bool ALIGN_EPI = false, bool SP2 = false>
; __device__ __forceinline__ void gemm_phase(PG8_LAS unsigned char* lds, const Gemm g, const Sched& S, const Epi& E) {
;     ...
;     for (int i = 0; i < 2; ++i) { int R, C; stage_rc(tid * 16 + i * 8192, R, C); const int Rb = Epi::PERM ? ((R & ~31) + perm32(R & 31)) : R;
;         voffA[i] = (unsigned)(R * K + C) * 2u; voffB[i] = (unsigned)(Rb * K + C) * 2u; }
;     const size_t kstep = (size_t)(BK * 2);
;     const size_t hstep = (size_t)HALF * K * 2;
;     const size_t tstep = 2 * hstep;
;     const unsigned ldsw = (unsigned)wid * 1024u;
;     const int aoff = lds_byte(wr * 64 + fr, fq * 8), boff = lds_byte(wc * 32 + fr, fq * 8);
;     ...
;         PG8_STAGE(PG8_SB(1, 0), cB + kstep, voffB); PG8_STAGE(PG8_SA(1, 0), cA + kstep, voffA); PG8_STAGE(PG8_SB(1, 1), cB + hstep + kstep, voffB);
;         PG8_WAIT_V(6); PG8_BAR;
.LBB0_137:
	s_and_b32 s23, s14, 3
	s_lshl_b32 s30, s1, 13
	s_lshl_b32 s31, s23, 5
	s_lshl_b32 s33, s23, 12
	s_add_u32 s26, s38, 0xc000000
	v_readlane_b32 s14, v254, 24
	v_readlane_b32 s12, v254, 52
	s_addc_u32 s27, s39, 0
	s_lshl_b32 s14, s12, 6
	s_add_u32 s40, s38, 0x200000
	s_addc_u32 s41, s39, 0
	s_add_u32 s42, s38, 0x240000
	s_addc_u32 s43, s39, 0
	s_add_i32 m0, s11, 0x18000
	v_lshl_add_u64 v[6:7], v[6:7], 0, s[36:37]
	global_load_lds_dwordx4 v[6:7], off
	v_lshl_add_u64 v[4:5], v[4:5], 0, s[36:37]
	s_add_i32 m0, s11, 0x1a000
	s_add_i32 s24, s11, 0x8000
	s_add_i32 s25, s11, 0xa000
	global_load_lds_dwordx4 v[4:5], off
	v_lshl_add_u64 v[0:1], v[0:1], 0, s[36:37]
	s_mov_b32 m0, s24
	s_add_u32 s28, s4, 0x40080
	global_load_lds_dwordx4 v[0:1], off
	v_lshl_add_u64 v[0:1], v[2:3], 0, s[36:37]
	s_mov_b32 m0, s25
	s_addc_u32 s29, s5, 0
	global_load_lds_dwordx4 v[0:1], off
	s_add_i32 m0, s11, 0x1c000
	v_lshl_add_u64 v[0:1], s[28:29], 0, v[198:199]
	global_load_lds_dwordx4 v[0:1], off
	v_lshl_add_u64 v[0:1], s[28:29], 0, v[194:195]
	s_add_i32 m0, s11, 0x1e000
	s_cmpk_lt_u32 s0, 0x100
	global_load_lds_dwordx4 v[0:1], off
	s_waitcnt vmcnt(8)
	s_barrier
	v_and_b32_e32 v0, 15, v8
	s_cselect_b64 s[44:45], -1, 0
	s_lshl_b32 s0, s1, 11
	v_bfe_u32 v203, v8, 4, 2
	v_lshl_or_b32 v247, s1, 6, v0
	s_lshl_b32 s1, s23, 9
	s_add_i32 s0, s0, 0
	v_lshlrev_b32_e32 v248, 4, v203
	s_add_i32 s0, s0, s1
	v_lshl_or_b32 v1, v0, 6, v248
	v_lshlrev_b32_e32 v0, 2, v0
	s_add_i32 s0, s0, 0x20000
	v_and_b32_e32 v2, 32, v0
	v_add_u32_e32 v250, s0, v0
	v_lshlrev_b32_e32 v0, 14, v9
	v_and_b32_e32 v0, 0xffff8000, v0
	v_bitop3_b32 v3, v1, s30, v2 bitop3:0xde
	v_bitop3_b32 v249, v1, s33, v2 bitop3:0xde
	v_lshl_add_u32 v0, v10, 11, v0
	v_and_b32_e32 v1, 1, v9
	v_readlane_b32 s15, v254, 25
	v_lshl_or_b32 v0, v1, 6, v0
	v_lshl_add_u32 v204, v11, 1, v0
	v_lshlrev_b32_e32 v0, 14, v13
	s_lshl_b64 s[46:47], s[14:15], 2
	s_lshl_b32 s14, s31, 1
	v_and_b32_e32 v0, 0xffff8000, v0
	v_writelane_b32 v254, s14, 24
	s_waitcnt vmcnt(6)
	v_lshl_add_u32 v0, v12, 11, v0
	v_and_b32_e32 v1, 1, v13
	v_writelane_b32 v254, s15, 25
	v_lshl_or_b32 v0, v1, 6, v0
	v_readlane_b32 s0, v254, 34
	v_lshlrev_b32_e32 v202, 3, v203
	v_lshl_add_u32 v251, v203, 6, v250
	v_mov_b32_e32 v205, v177
	v_lshl_add_u32 v206, v14, 1, v0
	v_mov_b32_e32 v207, v177
	s_mov_b32 s28, 0
	v_add_u32_e32 v245, 0, v3
	v_readlane_b32 s29, v254, 11
	s_mov_b32 s30, s0
	s_mov_b64 s[18:19], 0x40000
	s_barrier
	v_readlane_b32 s1, v254, 35
	s_branch .LBB0_140

; #define PG8_STAGE(bufoff, gbase, voff) do { _Pragma("unroll") for (int _i = 0; _i < 2; ++_i) \
;         __builtin_amdgcn_global_load_lds((const unsigned*)((const char*)(gbase) + (voff)[_i]), (PG8_LAS unsigned*)(lds + (bufoff) + ldsw + _i * 8192), 16, 0, 0); } while (0)
; #define PG8_WAIT_V(n) asm volatile("s_waitcnt vmcnt(" #n ")" ::: "memory")
; #define PG8_BAR __builtin_amdgcn_s_barrier()
; template <class Epi, class Sched, bool ALIGN_EPI = false, bool SP2 = false>
; __device__ __forceinline__ void gemm_phase(PG8_LAS unsigned char* lds, const Gemm g, const Sched& S, const Epi& E) {
;     ...
;     for (int i = 0; i < 2; ++i) { int R, C; stage_rc(tid * 16 + i * 8192, R, C); const int Rb = Epi::PERM ? ((R & ~31) + perm32(R & 31)) : R;
;         voffA[i] = (unsigned)(R * K + C) * 2u; voffB[i] = (unsigned)(Rb * K + C) * 2u; }
;     const size_t kstep = (size_t)(BK * 2);
;     const size_t hstep = (size_t)HALF * K * 2;
;     const size_t tstep = 2 * hstep;
;     const unsigned ldsw = (unsigned)wid * 1024u;
;     const int aoff = lds_byte(wr * 64 + fr, fq * 8), boff = lds_byte(wc * 32 + fr, fq * 8);
;     ...
;         PG8_STAGE(PG8_SB(1, 0), cB + kstep, voffB); PG8_STAGE(PG8_SA(1, 0), cA + kstep, voffA); PG8_STAGE(PG8_SB(1, 1), cB + hstep + kstep, voffB);
;         PG8_WAIT_V(6); PG8_BAR;
.LBB0_255:
	s_and_b32 s11, s11, 3
	s_lshl_b32 s14, s10, 13
	s_lshl_b32 s58, s11, 5
	s_lshl_b32 s22, s11, 12
	s_add_u32 s40, s38, 0x8000000
	s_addc_u32 s41, s39, 0
	s_add_u32 s42, s38, 0xa000000
	s_addc_u32 s43, s39, 0
	s_add_i32 m0, s54, 0x18000
	v_lshl_add_u64 v[6:7], v[6:7], 0, s[36:37]
	global_load_lds_dwordx4 v[6:7], off
	v_lshl_add_u64 v[4:5], v[4:5], 0, s[36:37]
	s_add_i32 m0, s54, 0x1a000
	s_add_i32 s59, s54, 0x8000
	s_add_i32 s62, s54, 0xa000
	global_load_lds_dwordx4 v[4:5], off
	v_lshl_add_u64 v[0:1], v[0:1], 0, s[36:37]
	s_mov_b32 m0, s59
	s_add_u32 s20, s0, 0x40080
	global_load_lds_dwordx4 v[0:1], off
	v_lshl_add_u64 v[0:1], v[2:3], 0, s[36:37]
	s_mov_b32 m0, s62
	s_addc_u32 s21, s1, 0
	global_load_lds_dwordx4 v[0:1], off
	s_add_i32 m0, s54, 0x1c000
	v_lshl_add_u64 v[0:1], s[20:21], 0, v[132:133]
	global_load_lds_dwordx4 v[0:1], off
	v_lshl_add_u64 v[0:1], s[20:21], 0, v[128:129]
	s_add_i32 m0, s54, 0x1e000
	s_cmpk_lt_u32 s3, 0x100
	global_load_lds_dwordx4 v[0:1], off
	s_waitcnt vmcnt(8)
	s_barrier
	v_and_b32_e32 v0, 15, v9
	s_cselect_b64 s[44:45], -1, 0
	s_lshl_b32 s3, s10, 11
	v_bfe_u32 v1, v9, 4, 2
	v_lshl_or_b32 v137, s10, 6, v0
	s_lshl_b32 s10, s11, 9
	s_add_i32 s3, s3, 0
	v_lshlrev_b32_e32 v2, 4, v1
	s_add_i32 s3, s3, s10
	v_lshl_or_b32 v3, v0, 6, v2
	v_lshlrev_b32_e32 v0, 2, v0
	s_add_i32 s3, s3, 0x20000
	v_and_b32_e32 v4, 32, v0
	v_add_u32_e32 v151, s3, v0
	v_lshlrev_b32_e32 v0, 14, v8
	v_and_b32_e32 v0, 0xffff8000, v0
	v_lshlrev_b32_e32 v136, 3, v1
	v_lshl_add_u32 v152, v1, 6, v151
	v_lshl_add_u32 v0, v10, 11, v0
	v_and_b32_e32 v1, 1, v8
	v_lshl_or_b32 v0, v1, 6, v0
	v_lshl_add_u32 v138, v11, 1, v0
	v_lshlrev_b32_e32 v0, 14, v13
	v_and_b32_e32 v0, 0xffff8000, v0
	s_waitcnt vmcnt(6)
	v_lshl_add_u32 v0, v12, 11, v0
	v_and_b32_e32 v1, 1, v13
	v_bitop3_b32 v5, v3, s14, v4 bitop3:0xde
	v_lshl_or_b32 v0, v1, 6, v0
	v_readlane_b32 s20, v254, 38
	v_bitop3_b32 v149, v3, s22, v4 bitop3:0xde
	v_or_b32_e32 v150, v137, v2
	v_mov_b32_e32 v139, v177
	v_lshl_add_u32 v140, v14, 1, v0
	v_mov_b32_e32 v141, v177
	s_mov_b32 s63, 0
	v_add_u32_e32 v153, 0, v5
	v_readlane_b32 s10, v254, 14
	s_mov_b32 s3, s20
	s_barrier
	v_readlane_b32 s21, v254, 39
	s_branch .LBB0_258

; #define PG8_STAGE(bufoff, gbase, voff) do { _Pragma("unroll") for (int _i = 0; _i < 2; ++_i) \
;         __builtin_amdgcn_global_load_lds((const unsigned*)((const char*)(gbase) + (voff)[_i]), (PG8_LAS unsigned*)(lds + (bufoff) + ldsw + _i * 8192), 16, 0, 0); } while (0)
; #define PG8_WAIT_V(n) asm volatile("s_waitcnt vmcnt(" #n ")" ::: "memory")
; #define PG8_BAR __builtin_amdgcn_s_barrier()
; template <class Epi, class Sched, bool ALIGN_EPI = false, bool SP2 = false>
; __device__ __forceinline__ void gemm_phase(PG8_LAS unsigned char* lds, const Gemm g, const Sched& S, const Epi& E) {
;     ...
;     for (int i = 0; i < 2; ++i) { int R, C; stage_rc(tid * 16 + i * 8192, R, C); const int Rb = Epi::PERM ? ((R & ~31) + perm32(R & 31)) : R;
;         voffA[i] = (unsigned)(R * K + C) * 2u; voffB[i] = (unsigned)(Rb * K + C) * 2u; }
;     const size_t kstep = (size_t)(BK * 2);
;     const size_t hstep = (size_t)HALF * K * 2;
;     const size_t tstep = 2 * hstep;
;     const unsigned ldsw = (unsigned)wid * 1024u;
;     const int aoff = lds_byte(wr * 64 + fr, fq * 8), boff = lds_byte(wc * 32 + fr, fq * 8);
;     ...
;         PG8_STAGE(PG8_SB(1, 0), cB + kstep, voffB); PG8_STAGE(PG8_SA(1, 0), cA + kstep, voffA); PG8_STAGE(PG8_SB(1, 1), cB + hstep + kstep, voffB);
;         PG8_WAIT_V(6); PG8_BAR;
.LBB0_548:
	s_add_u32 s8, s0, 0x6000000
	s_addc_u32 s9, s1, 0
	v_bfe_u32 v15, v14, 4, 2
	s_add_u32 s16, s0, 0x100000
	v_and_b32_e32 v16, 15, v14
	v_lshlrev_b32_e32 v18, 4, v15
	v_lshlrev_b32_e32 v14, 2, v14
	s_addc_u32 s17, s1, 0
	s_and_b32 s25, s14, 3
	v_lshl_or_b32 v200, s5, 6, v16
	v_lshl_or_b32 v16, v16, 6, v18
	s_lshl_b32 s0, s5, 13
	v_and_b32_e32 v14, 32, v14
	s_add_i32 m0, s21, 0x18000
	v_lshl_add_u64 v[6:7], v[6:7], 0, s[36:37]
	v_bitop3_b32 v18, v16, s0, v14 bitop3:0xde
	s_lshl_b32 s0, s25, 12
	global_load_lds_dwordx4 v[6:7], off
	v_lshl_add_u64 v[4:5], v[4:5], 0, s[36:37]
	s_add_i32 m0, s21, 0x1a000
	s_add_i32 s28, s21, 0x8000
	s_add_i32 s29, s21, 0xa000
	v_bitop3_b32 v201, v16, s0, v14 bitop3:0xde
	global_load_lds_dwordx4 v[4:5], off
	v_lshl_add_u64 v[0:1], v[0:1], 0, s[36:37]
	s_mov_b32 m0, s28
	s_add_u32 s0, s48, 0x40080
	global_load_lds_dwordx4 v[0:1], off
	v_lshl_add_u64 v[0:1], v[2:3], 0, s[36:37]
	s_mov_b32 m0, s29
	s_addc_u32 s1, s49, 0
	global_load_lds_dwordx4 v[0:1], off
	s_add_i32 m0, s21, 0x1c000
	v_lshl_add_u64 v[0:1], s[0:1], 0, v[156:157]
	global_load_lds_dwordx4 v[0:1], off
	v_lshl_add_u64 v[0:1], s[0:1], 0, v[152:153]
	s_add_i32 m0, s21, 0x1e000
	v_lshlrev_b32_e32 v17, 3, v15
	global_load_lds_dwordx4 v[0:1], off
	s_waitcnt vmcnt(8)
	s_barrier
	v_lshlrev_b32_e32 v0, 14, v8
	v_and_b32_e32 v0, 0xffff8000, v0
	v_lshl_add_u32 v0, v9, 11, v0
	v_and_b32_e32 v1, 1, v8
	v_lshl_or_b32 v0, v1, 6, v0
	v_lshl_add_u32 v160, v10, 1, v0
	v_lshlrev_b32_e32 v0, 14, v12
	v_and_b32_e32 v0, 0xffff8000, v0
	s_waitcnt vmcnt(6)
	v_lshl_add_u32 v0, v11, 11, v0
	v_and_b32_e32 v1, 1, v12
	s_cmpk_lt_u32 s4, 0x100
	v_lshl_or_b32 v0, v1, 6, v0
	v_readlane_b32 s4, v254, 44
	v_lshl_or_b32 v202, s25, 5, v17
	s_cselect_b64 s[26:27], -1, 0
	s_mov_b32 s30, 0
	v_cmp_eq_u32_e64 s[0:1], 0, v15
	v_mov_b32_e32 v161, v177
	v_lshl_add_u32 v162, v13, 1, v0
	v_mov_b32_e32 v163, v177
	v_add_u32_e32 v203, 0, v18
	v_readlane_b32 s14, v254, 17
	s_mov_b32 s31, s4
	s_barrier
	v_readlane_b32 s5, v254, 45
	s_branch .LBB0_551

; #define PG8_STAGE(bufoff, gbase, voff) do { _Pragma("unroll") for (int _i = 0; _i < 2; ++_i) \
;         __builtin_amdgcn_global_load_lds((const unsigned*)((const char*)(gbase) + (voff)[_i]), (PG8_LAS unsigned*)(lds + (bufoff) + ldsw + _i * 8192), 16, 0, 0); } while (0)
; #define PG8_WAIT_V(n) asm volatile("s_waitcnt vmcnt(" #n ")" ::: "memory")
; #define PG8_BAR __builtin_amdgcn_s_barrier()
; template <class Epi, class Sched, bool ALIGN_EPI = false, bool SP2 = false>
; __device__ __forceinline__ void gemm_phase(PG8_LAS unsigned char* lds, const Gemm g, const Sched& S, const Epi& E) {
;     ...
;     for (int i = 0; i < 2; ++i) { int R, C; stage_rc(tid * 16 + i * 8192, R, C); const int Rb = Epi::PERM ? ((R & ~31) + perm32(R & 31)) : R;
;         voffA[i] = (unsigned)(R * K + C) * 2u; voffB[i] = (unsigned)(Rb * K + C) * 2u; }
;     const size_t kstep = (size_t)(BK * 2);
;     const size_t hstep = (size_t)HALF * K * 2;
;     const size_t tstep = 2 * hstep;
;     const unsigned ldsw = (unsigned)wid * 1024u;
;     const int aoff = lds_byte(wr * 64 + fr, fq * 8), boff = lds_byte(wc * 32 + fr, fq * 8);
;     ...
;         PG8_STAGE(PG8_SB(1, 0), cB + kstep, voffB); PG8_STAGE(PG8_SA(1, 0), cA + kstep, voffA); PG8_STAGE(PG8_SB(1, 1), cB + hstep + kstep, voffB);
;         PG8_WAIT_V(6); PG8_BAR;
.LBB0_649:
	s_add_u32 s6, s0, 0x100000
	s_addc_u32 s7, s1, 0
	s_add_u32 s8, s0, 0x8000000
	s_addc_u32 s9, s1, 0
	s_and_b32 s27, s16, 3
	s_add_i32 m0, s21, 0x18000
	v_lshl_add_u64 v[6:7], v[6:7], 0, s[36:37]
	s_lshl_b32 s16, s26, 13
	s_lshl_b32 s30, s27, 5
	s_lshl_b32 s17, s27, 12
	global_load_lds_dwordx4 v[6:7], off
	v_lshl_add_u64 v[4:5], v[4:5], 0, s[36:37]
	s_add_i32 m0, s21, 0x1a000
	s_add_i32 s25, s21, 0x8000
	s_add_i32 s28, s21, 0xa000
	global_load_lds_dwordx4 v[4:5], off
	v_lshl_add_u64 v[0:1], v[0:1], 0, s[36:37]
	s_mov_b32 m0, s25
	s_add_u32 s0, s46, 0x40080
	global_load_lds_dwordx4 v[0:1], off
	v_lshl_add_u64 v[0:1], v[2:3], 0, s[36:37]
	s_mov_b32 m0, s28
	s_addc_u32 s1, s47, 0
	global_load_lds_dwordx4 v[0:1], off
	s_add_i32 m0, s21, 0x1c000
	v_lshl_add_u64 v[0:1], s[0:1], 0, v[132:133]
	global_load_lds_dwordx4 v[0:1], off
	v_lshl_add_u64 v[0:1], s[0:1], 0, v[128:129]
	s_add_i32 m0, s21, 0x1e000
	v_bfe_u32 v2, v8, 4, 2
	global_load_lds_dwordx4 v[0:1], off
	s_waitcnt vmcnt(8)
	s_barrier
	v_and_b32_e32 v1, 15, v8
	v_lshlrev_b32_e32 v147, 4, v2
	v_lshl_or_b32 v146, s26, 6, v1
	v_lshl_or_b32 v3, v1, 6, v147
	v_lshlrev_b32_e32 v1, 2, v1
	v_and_b32_e32 v4, 32, v1
	s_cmpk_lt_u32 s14, 0x100
	v_bitop3_b32 v5, v3, s16, v4 bitop3:0xde
	v_bitop3_b32 v148, v3, s17, v4 bitop3:0xde
	s_cselect_b64 s[16:17], -1, 0
	s_lshl_b32 s0, s26, 11
	s_lshl_b32 s1, s27, 9
	s_add_i32 s0, s0, 0
	s_add_i32 s0, s0, s1
	s_add_i32 s0, s0, 0x20000
	v_add_u32_e32 v149, s0, v1
	v_lshlrev_b32_e32 v1, 14, v9
	v_and_b32_e32 v1, 0xffff8000, v1
	v_lshlrev_b32_e32 v0, 3, v2
	v_lshl_add_u32 v150, v2, 6, v149
	v_lshl_add_u32 v1, v10, 11, v1
	v_and_b32_e32 v2, 1, v9
	v_lshl_or_b32 v1, v2, 6, v1
	v_readlane_b32 s0, v254, 24
	v_lshl_add_u32 v136, v11, 1, v1
	v_lshlrev_b32_e32 v1, 14, v13
	v_readlane_b32 s1, v254, 25
	s_lshl_b32 s0, s30, 1
	v_and_b32_e32 v1, 0xffff8000, v1
	v_writelane_b32 v254, s0, 24
	s_waitcnt vmcnt(6)
	v_lshl_add_u32 v1, v12, 11, v1
	v_and_b32_e32 v2, 1, v13
	v_writelane_b32 v254, s1, 25
	v_lshl_or_b32 v1, v2, 6, v1
	v_readlane_b32 s0, v254, 30
	v_mov_b32_e32 v137, v177
	v_lshl_add_u32 v138, v14, 1, v1
	v_mov_b32_e32 v139, v177
	s_mov_b32 s29, 0
	v_add_u32_e32 v151, 0, v5
	v_lshlrev_b32_e32 v140, 1, v0
	v_readlane_b32 s30, v254, 8
	s_mov_b32 s31, s0
	s_barrier
	v_readlane_b32 s1, v254, 31
	s_branch .LBB0_652

; #define PG8_STAGE(bufoff, gbase, voff) do { _Pragma("unroll") for (int _i = 0; _i < 2; ++_i) \
;         __builtin_amdgcn_global_load_lds((const unsigned*)((const char*)(gbase) + (voff)[_i]), (PG8_LAS unsigned*)(lds + (bufoff) + ldsw + _i * 8192), 16, 0, 0); } while (0)
; #define PG8_WAIT_V(n) asm volatile("s_waitcnt vmcnt(" #n ")" ::: "memory")
; #define PG8_BAR __builtin_amdgcn_s_barrier()
; template <class Epi, class Sched, bool ALIGN_EPI = false, bool SP2 = false>
; __device__ __forceinline__ void gemm_phase(PG8_LAS unsigned char* lds, const Gemm g, const Sched& S, const Epi& E) {
;     ...
;     for (int i = 0; i < 2; ++i) { int R, C; stage_rc(tid * 16 + i * 8192, R, C); const int Rb = Epi::PERM ? ((R & ~31) + perm32(R & 31)) : R;
;         voffA[i] = (unsigned)(R * K + C) * 2u; voffB[i] = (unsigned)(Rb * K + C) * 2u; }
;     const size_t kstep = (size_t)(BK * 2);
;     const size_t hstep = (size_t)HALF * K * 2;
;     const size_t tstep = 2 * hstep;
;     const unsigned ldsw = (unsigned)wid * 1024u;
;     const int aoff = lds_byte(wr * 64 + fr, fq * 8), boff = lds_byte(wc * 32 + fr, fq * 8);
;     ...
;         PG8_STAGE(PG8_SB(1, 0), cB + kstep, voffB); PG8_STAGE(PG8_SA(1, 0), cA + kstep, voffA); PG8_STAGE(PG8_SB(1, 1), cB + hstep + kstep, voffB);
;         PG8_WAIT_V(6); PG8_BAR;
.LBB0_734:
	s_add_u32 s16, s0, 0x6000000
	s_addc_u32 s17, s1, 0
	s_add_u32 s26, s0, 0x100000
	s_addc_u32 s27, s1, 0
	v_readlane_b32 s40, v252, 0
	v_bfe_u32 v15, v14, 4, 2
	s_cmp_eq_u32 s18, 3
	v_readlane_b32 s41, v252, 1
	v_readlane_b32 s46, v252, 6
	v_readlane_b32 s47, v252, 7
	v_and_b32_e32 v16, 15, v14
	v_lshlrev_b32_e32 v18, 4, v15
	v_lshlrev_b32_e32 v14, 2, v14
	s_cselect_b32 s41, s47, 0
	s_cselect_b32 s40, s46, 0
	s_and_b32 s28, s14, 3
	v_lshl_or_b32 v204, s7, 6, v16
	v_lshl_or_b32 v16, v16, 6, v18
	s_lshl_b32 s0, s7, 13
	v_and_b32_e32 v14, 32, v14
	s_add_i32 m0, s21, 0x18000
	v_lshl_add_u64 v[6:7], v[6:7], 0, s[36:37]
	v_bitop3_b32 v18, v16, s0, v14 bitop3:0xde
	s_lshl_b32 s0, s28, 12
	global_load_lds_dwordx4 v[6:7], off
	v_lshl_add_u64 v[4:5], v[4:5], 0, s[36:37]
	s_add_i32 m0, s21, 0x1a000
	s_add_i32 s29, s21, 0x8000
	s_add_i32 s30, s21, 0xa000
	v_bitop3_b32 v205, v16, s0, v14 bitop3:0xde
	global_load_lds_dwordx4 v[4:5], off
	v_lshl_add_u64 v[0:1], v[0:1], 0, s[36:37]
	s_mov_b32 m0, s29
	s_add_u32 s0, s4, 0x100080
	global_load_lds_dwordx4 v[0:1], off
	v_lshl_add_u64 v[0:1], v[2:3], 0, s[36:37]
	s_mov_b32 m0, s30
	s_addc_u32 s1, s5, 0
	global_load_lds_dwordx4 v[0:1], off
	s_add_i32 m0, s21, 0x1c000
	v_lshl_add_u64 v[0:1], s[0:1], 0, v[160:161]
	global_load_lds_dwordx4 v[0:1], off
	v_lshl_add_u64 v[0:1], s[0:1], 0, v[156:157]
	s_add_i32 m0, s21, 0x1e000
	v_readlane_b32 s42, v252, 2
	global_load_lds_dwordx4 v[0:1], off
	s_waitcnt vmcnt(8)
	s_barrier
	v_lshlrev_b32_e32 v0, 16, v8
	v_and_b32_e32 v0, 0xfffe0000, v0
	v_lshl_add_u32 v0, v9, 13, v0
	v_and_b32_e32 v1, 1, v8
	v_lshl_or_b32 v0, v1, 6, v0
	v_lshl_add_u32 v164, v10, 1, v0
	v_lshlrev_b32_e32 v0, 16, v12
	v_readlane_b32 s43, v252, 3
	s_cmpk_lt_u32 s6, 0x100
	v_and_b32_e32 v0, 0xfffe0000, v0
	v_readlane_b32 s44, v252, 4
	v_readlane_b32 s45, v252, 5
	s_waitcnt vmcnt(6)
	s_cselect_b64 s[42:43], -1, 0
	s_cmp_eq_u64 s[40:41], 0
	v_lshl_add_u32 v0, v11, 13, v0
	v_and_b32_e32 v1, 1, v12
	v_lshlrev_b32_e32 v17, 3, v15
	s_cselect_b64 s[44:45], -1, 0
	s_cmp_lg_u64 s[40:41], 0
	v_lshl_or_b32 v0, v1, 6, v0
	v_readlane_b32 s6, v254, 44
	s_mov_b32 s25, 0
	v_lshl_or_b32 v206, s28, 5, v17
	v_cmp_eq_u32_e64 s[0:1], 0, v15
	s_cselect_b64 s[46:47], -1, 0
	v_mov_b32_e32 v165, v177
	v_lshl_add_u32 v166, v13, 1, v0
	v_mov_b32_e32 v167, v177
	v_add_u32_e32 v207, 0, v18
	v_readlane_b32 s14, v254, 17
	s_mov_b32 s31, s6
	s_barrier
	v_readlane_b32 s7, v254, 45
	s_branch .LBB0_737
